# widened MERGED stores marked write-through (sc1) so the grid barrier before the W_o phase has no dirty L2 lines to write back
# baseline (speedup 1.0000x reference)
; __device__ __forceinline__ u32x2 pk4(f32x4 v) { u32x2 r; r.x = pk_bf16(v[0], v[1]); r.y = pk_bf16(v[2], v[3]); return r; }
; __device__ __forceinline__ f32x4 unpk4(u32x2 v) { return (f32x4){bf_lo(v.x), bf_hi(v.x), bf_lo(v.y), bf_hi(v.y)}; }
; __device__ __forceinline__ void tie4(u32x2 (&d)[4]) { asm volatile("" : "+v"(d[0]), "+v"(d[1]), "+v"(d[2]), "+v"(d[3])); }
;     template <int POS> __device__ __forceinline__ void run(f32x4 (&acc)[2][2][4][2], const Unit& u, const bf16_t* F, int wr, int wc, int fr, int fq) const {
;         const int w4 = wr * 4 + wc, lane = fq * 16 + fr;
;         const u32x2* s0 = (const u32x2*)F + native_slot(u.pm, u.pn, w4, 0, 0, 0, 0, lane);
;         u32x2 ga[2][4];
;         ld4(ga[0], s0); ld4(ga[1], s0 + 256);
; #pragma unroll
;         for (int e = 0; e < 8; ++e) {
;             if (POS < 2) { if (e < 7) asm volatile("s_waitcnt vmcnt(4)" ::: "memory"); else asm volatile("s_waitcnt vmcnt(0)" ::: "memory"); }
;             else { if (e == 0) asm volatile("s_waitcnt vmcnt(4)" ::: "memory"); else if (e < 7) asm volatile("s_waitcnt vmcnt(8)" ::: "memory"); else asm volatile("s_waitcnt vmcnt(4)" ::: "memory"); }
;             tie4(ga[e & 1]);
;             const int ai = e >> 2, m = e & 3;
; #pragma unroll
;             for (int k = 0; k < 4; ++k) { const int bj = k >> 1, n = k & 1;
;                 const f32x4 f = unpk4(ga[e & 1][k]);
;                 if (POS < 2) acc[ai][bj][m][n] *= f;
;                 else *(u32x2*)(MERGED + (size_t)(u.pm * 256 + ai * 128 + wr * 64 + m * 16 + fr) * 1024 + u.pn * 256 + bj * 128 + wc * 32 + n * 16 + fq * 4) = pk4(f * acc[ai][bj][m][n]);
;             }
;             if (e + 2 < 8) ld4(ga[e & 1], s0 + (e + 2) * 256);
;         }
.LBB0_548:
	v_mbcnt_lo_u32_b32 v206, -1, 0
	v_mbcnt_hi_u32_b32 v206, -1, v206
	v_lshrrev_b32_e32 v206, 1, v206
	v_and_b32_e32 v206, 24, v206
	v_mov_b32_e32 v207, 0
	s_cmp_gt_i32 s68, 1
	s_cselect_b64 s[66:67], -1, 0
	s_mov_b64 s[28:29], -1
	s_and_b64 vcc, exec, s[66:67]
	s_cbranch_vccz .LBB0_551
	s_lshl_b32 s4, s64, 2
	s_add_i32 s28, s4, s76
	s_ashr_i32 s29, s28, 31
	s_lshl_b64 s[28:29], s[28:29], 17
	v_lshl_add_u64 v[144:145], v[134:135], 0, s[28:29]
	global_load_dwordx2 v[142:143], v[144:145], off nt
	global_load_dwordx2 v[152:153], v[144:145], off offset:512 nt
	global_load_dwordx2 v[154:155], v[144:145], off offset:1024 nt
	global_load_dwordx2 v[156:157], v[144:145], off offset:1536 nt
	v_lshl_add_u64 v[158:159], v[144:145], 0, s[20:21]
	global_load_dwordx2 v[160:161], v[158:159], off nt
	global_load_dwordx2 v[162:163], v[158:159], off offset:512 nt
	global_load_dwordx2 v[164:165], v[158:159], off offset:1024 nt
	global_load_dwordx2 v[158:159], v[158:159], off offset:1536 nt
	s_waitcnt vmcnt(4)
	s_lshl_b32 s4, s64, 8
	v_lshlrev_b32_e32 v166, 16, v142
	v_and_b32_e32 v167, 0xffff0000, v142
	v_lshlrev_b32_e32 v142, 16, v143
	v_and_b32_e32 v143, 0xffff0000, v143
	v_pk_mul_f32 v[142:143], v[126:127], v[142:143]
	v_pk_mul_f32 v[166:167], v[124:125], v[166:167]
	s_lshl_b32 s28, s76, 8
	v_cvt_pk_bf16_f32 v166, v166, v167
	v_cvt_pk_bf16_f32 v167, v142, v143
	v_add_u32_e32 v142, s4, v146
	v_ashrrev_i32_e32 v143, 31, v142
	v_lshlrev_b64 v[168:169], 11, v[142:143]
	s_ashr_i32 s29, s28, 31
	v_lshl_add_u64 v[168:169], s[14:15], 0, v[168:169]
	s_lshl_b64 s[28:29], s[28:29], 1
	v_lshl_add_u64 v[168:169], v[168:169], 0, s[28:29]
	s_mov_b32 s39, s5
	v_lshl_add_u64 v[168:169], v[168:169], 0, s[38:39]
	v_mov_b32_e32 v141, v133
	v_lshl_add_u64 v[168:169], v[168:169], 0, v[140:141]
	v_mov_b32_e32 v172, v166
	v_mov_b32_e32 v173, v167
	v_lshlrev_b32_e32 v166, 16, v152
	v_and_b32_e32 v167, 0xffff0000, v152
	v_lshlrev_b32_e32 v152, 16, v153
	v_and_b32_e32 v153, 0xffff0000, v153
	v_pk_mul_f32 v[152:153], v[122:123], v[152:153]
	v_pk_mul_f32 v[166:167], v[120:121], v[166:167]
	s_nop 0
	v_cvt_pk_bf16_f32 v166, v166, v167
	v_cvt_pk_bf16_f32 v167, v152, v153
	v_lshlrev_b32_e32 v152, 16, v154
	v_and_b32_e32 v153, 0xffff0000, v154
	v_lshlrev_b32_e32 v154, 16, v155
	v_and_b32_e32 v155, 0xffff0000, v155
	v_pk_mul_f32 v[154:155], v[94:95], v[154:155]
	v_pk_mul_f32 v[152:153], v[92:93], v[152:153]
	v_mov_b32_e32 v174, v166
	v_mov_b32_e32 v175, v167
	v_cvt_pk_bf16_f32 v152, v152, v153
	v_cvt_pk_bf16_f32 v153, v154, v155
	v_mov_b32_e32 v176, v152
	v_mov_b32_e32 v177, v153
	v_lshlrev_b32_e32 v152, 16, v156
	v_and_b32_e32 v153, 0xffff0000, v156
	v_lshlrev_b32_e32 v154, 16, v157
	v_and_b32_e32 v155, 0xffff0000, v157
	v_pk_mul_f32 v[154:155], v[90:91], v[154:155]
	v_pk_mul_f32 v[152:153], v[88:89], v[152:153]
	s_nop 0
	v_cvt_pk_bf16_f32 v152, v152, v153
	v_cvt_pk_bf16_f32 v153, v154, v155
	v_mov_b32_e32 v178, v152
	v_mov_b32_e32 v179, v153
	s_nop 1
	v_permlane32_swap_b32_e32 v172, v174
	v_permlane32_swap_b32_e32 v173, v175
	v_permlane32_swap_b32_e32 v176, v178
	v_permlane32_swap_b32_e32 v177, v179
	v_permlane16_swap_b32_e32 v172, v174
	v_permlane16_swap_b32_e32 v173, v175
	v_permlane16_swap_b32_e32 v176, v178
	v_permlane16_swap_b32_e32 v177, v179
	v_lshl_add_u64 v[204:205], v[168:169], 0, v[206:207]
	global_store_dwordx4 v[204:205], v[172:175], off sc1
	global_store_dwordx4 v[204:205], v[176:179], off offset:256 sc1
	v_lshl_add_u64 v[152:153], v[144:145], 0, s[42:43]
	global_load_dwordx2 v[154:155], v[152:153], off nt
	global_load_dwordx2 v[156:157], v[152:153], off offset:512 nt
	global_load_dwordx2 v[166:167], v[152:153], off offset:1024 nt
	global_load_dwordx2 v[152:153], v[152:153], off offset:1536 nt
	s_waitcnt vmcnt(6)
	s_nop 0
	v_lshlrev_b32_e32 v168, 16, v160
	v_and_b32_e32 v169, 0xffff0000, v160
	v_lshlrev_b32_e32 v160, 16, v161
	v_and_b32_e32 v161, 0xffff0000, v161
	v_pk_mul_f32 v[160:161], v[118:119], v[160:161]
	v_pk_mul_f32 v[168:169], v[116:117], v[168:169]
	s_nop 0
	v_cvt_pk_bf16_f32 v168, v168, v169
	v_cvt_pk_bf16_f32 v169, v160, v161
	v_add_u32_e32 v160, s4, v148
	v_ashrrev_i32_e32 v161, 31, v160
	v_lshlrev_b64 v[160:161], 11, v[160:161]
	v_lshl_add_u64 v[160:161], s[14:15], 0, v[160:161]
	v_lshl_add_u64 v[160:161], v[160:161], 0, s[28:29]
	v_lshl_add_u64 v[160:161], v[160:161], 0, s[38:39]
	v_lshl_add_u64 v[160:161], v[160:161], 0, v[140:141]
	v_mov_b32_e32 v180, v168
	v_mov_b32_e32 v181, v169
	v_lshlrev_b32_e32 v168, 16, v162
	v_and_b32_e32 v169, 0xffff0000, v162
	v_lshlrev_b32_e32 v162, 16, v163
	v_and_b32_e32 v163, 0xffff0000, v163
	v_pk_mul_f32 v[162:163], v[114:115], v[162:163]
	v_pk_mul_f32 v[168:169], v[112:113], v[168:169]
	s_nop 0
	v_cvt_pk_bf16_f32 v168, v168, v169
	v_cvt_pk_bf16_f32 v169, v162, v163
	v_lshlrev_b32_e32 v162, 16, v164
	v_and_b32_e32 v163, 0xffff0000, v164
	v_lshlrev_b32_e32 v164, 16, v165
	v_and_b32_e32 v165, 0xffff0000, v165
	v_pk_mul_f32 v[164:165], v[86:87], v[164:165]
	v_pk_mul_f32 v[162:163], v[84:85], v[162:163]
	v_mov_b32_e32 v182, v168
	v_mov_b32_e32 v183, v169
	v_cvt_pk_bf16_f32 v162, v162, v163
	v_cvt_pk_bf16_f32 v163, v164, v165
	v_mov_b32_e32 v184, v162
	v_mov_b32_e32 v185, v163
	v_lshlrev_b32_e32 v162, 16, v158
	v_and_b32_e32 v163, 0xffff0000, v158
	v_lshlrev_b32_e32 v158, 16, v159
	v_and_b32_e32 v159, 0xffff0000, v159
	v_pk_mul_f32 v[158:159], v[82:83], v[158:159]
	v_pk_mul_f32 v[162:163], v[80:81], v[162:163]
	s_nop 0
	v_cvt_pk_bf16_f32 v162, v162, v163
	v_cvt_pk_bf16_f32 v163, v158, v159
	v_mov_b32_e32 v186, v162
	v_mov_b32_e32 v187, v163
	s_nop 1
	v_permlane32_swap_b32_e32 v180, v182
	v_permlane32_swap_b32_e32 v181, v183
	v_permlane32_swap_b32_e32 v184, v186
	v_permlane32_swap_b32_e32 v185, v187
	v_permlane16_swap_b32_e32 v180, v182
	v_permlane16_swap_b32_e32 v181, v183
	v_permlane16_swap_b32_e32 v184, v186
	v_permlane16_swap_b32_e32 v185, v187
	v_lshl_add_u64 v[204:205], v[160:161], 0, v[206:207]
	global_store_dwordx4 v[204:205], v[180:183], off sc1
	global_store_dwordx4 v[204:205], v[184:187], off offset:256 sc1
	v_lshl_add_u64 v[158:159], v[144:145], 0, s[44:45]
	global_load_dwordx2 v[160:161], v[158:159], off nt
	global_load_dwordx2 v[162:163], v[158:159], off offset:512 nt
	global_load_dwordx2 v[164:165], v[158:159], off offset:1024 nt
	global_load_dwordx2 v[158:159], v[158:159], off offset:1536 nt
	s_waitcnt vmcnt(6)
; __device__ __forceinline__ u32x2 pk4(f32x4 v) { u32x2 r; r.x = pk_bf16(v[0], v[1]); r.y = pk_bf16(v[2], v[3]); return r; }
; __device__ __forceinline__ f32x4 unpk4(u32x2 v) { return (f32x4){bf_lo(v.x), bf_hi(v.x), bf_lo(v.y), bf_hi(v.y)}; }
; __device__ __forceinline__ void tie4(u32x2 (&d)[4]) { asm volatile("" : "+v"(d[0]), "+v"(d[1]), "+v"(d[2]), "+v"(d[3])); }
;     template <int POS> __device__ __forceinline__ void run(f32x4 (&acc)[2][2][4][2], const Unit& u, const bf16_t* F, int wr, int wc, int fr, int fq) const {
;     ...
; #pragma unroll
;         for (int e = 0; e < 8; ++e) {
;             if (POS < 2) { if (e < 7) asm volatile("s_waitcnt vmcnt(4)" ::: "memory"); else asm volatile("s_waitcnt vmcnt(0)" ::: "memory"); }
;             else { if (e == 0) asm volatile("s_waitcnt vmcnt(4)" ::: "memory"); else if (e < 7) asm volatile("s_waitcnt vmcnt(8)" ::: "memory"); else asm volatile("s_waitcnt vmcnt(4)" ::: "memory"); }
;             tie4(ga[e & 1]);
;             const int ai = e >> 2, m = e & 3;
; #pragma unroll
;             for (int k = 0; k < 4; ++k) { const int bj = k >> 1, n = k & 1;
;                 const f32x4 f = unpk4(ga[e & 1][k]);
;                 if (POS < 2) acc[ai][bj][m][n] *= f;
;                 else *(u32x2*)(MERGED + (size_t)(u.pm * 256 + ai * 128 + wr * 64 + m * 16 + fr) * 1024 + u.pn * 256 + bj * 128 + wc * 32 + n * 16 + fq * 4) = pk4(f * acc[ai][bj][m][n]);
;             }
;             if (e + 2 < 8) ld4(ga[e & 1], s0 + (e + 2) * 256);
;         }
	s_nop 0
	v_lshlrev_b32_e32 v168, 16, v154
	v_and_b32_e32 v169, 0xffff0000, v154
	v_lshlrev_b32_e32 v154, 16, v155
	v_and_b32_e32 v155, 0xffff0000, v155
	v_pk_mul_f32 v[154:155], v[110:111], v[154:155]
	v_pk_mul_f32 v[168:169], v[108:109], v[168:169]
	s_nop 0
	v_cvt_pk_bf16_f32 v168, v168, v169
	v_cvt_pk_bf16_f32 v169, v154, v155
	v_add_u32_e32 v154, s4, v149
	v_ashrrev_i32_e32 v155, 31, v154
	v_lshlrev_b64 v[154:155], 11, v[154:155]
	v_lshl_add_u64 v[154:155], s[14:15], 0, v[154:155]
	v_lshl_add_u64 v[154:155], v[154:155], 0, s[28:29]
	v_lshl_add_u64 v[154:155], v[154:155], 0, s[38:39]
	v_lshl_add_u64 v[154:155], v[154:155], 0, v[140:141]
	v_mov_b32_e32 v188, v168
	v_mov_b32_e32 v189, v169
	v_lshlrev_b32_e32 v168, 16, v156
	v_and_b32_e32 v169, 0xffff0000, v156
	v_lshlrev_b32_e32 v156, 16, v157
	v_and_b32_e32 v157, 0xffff0000, v157
	v_pk_mul_f32 v[156:157], v[106:107], v[156:157]
	v_pk_mul_f32 v[168:169], v[104:105], v[168:169]
	s_nop 0
	v_cvt_pk_bf16_f32 v168, v168, v169
	v_cvt_pk_bf16_f32 v169, v156, v157
	v_lshlrev_b32_e32 v156, 16, v166
	v_and_b32_e32 v157, 0xffff0000, v166
	v_lshlrev_b32_e32 v166, 16, v167
	v_and_b32_e32 v167, 0xffff0000, v167
	v_pk_mul_f32 v[166:167], v[78:79], v[166:167]
	v_pk_mul_f32 v[156:157], v[76:77], v[156:157]
	v_mov_b32_e32 v190, v168
	v_mov_b32_e32 v191, v169
	v_cvt_pk_bf16_f32 v156, v156, v157
	v_cvt_pk_bf16_f32 v157, v166, v167
	v_mov_b32_e32 v192, v156
	v_mov_b32_e32 v193, v157
	v_lshlrev_b32_e32 v156, 16, v152
	v_and_b32_e32 v157, 0xffff0000, v152
	v_lshlrev_b32_e32 v152, 16, v153
	v_and_b32_e32 v153, 0xffff0000, v153
	v_pk_mul_f32 v[152:153], v[74:75], v[152:153]
	v_pk_mul_f32 v[156:157], v[72:73], v[156:157]
	s_nop 0
	v_cvt_pk_bf16_f32 v156, v156, v157
	v_cvt_pk_bf16_f32 v157, v152, v153
	v_mov_b32_e32 v194, v156
	v_mov_b32_e32 v195, v157
	s_nop 1
	v_permlane32_swap_b32_e32 v188, v190
	v_permlane32_swap_b32_e32 v189, v191
	v_permlane32_swap_b32_e32 v192, v194
	v_permlane32_swap_b32_e32 v193, v195
	v_permlane16_swap_b32_e32 v188, v190
	v_permlane16_swap_b32_e32 v189, v191
	v_permlane16_swap_b32_e32 v192, v194
	v_permlane16_swap_b32_e32 v193, v195
	v_lshl_add_u64 v[204:205], v[154:155], 0, v[206:207]
	global_store_dwordx4 v[204:205], v[188:191], off sc1
	global_store_dwordx4 v[204:205], v[192:195], off offset:256 sc1
	v_lshl_add_u64 v[152:153], v[144:145], 0, s[46:47]
	global_load_dwordx2 v[154:155], v[152:153], off nt
	global_load_dwordx2 v[156:157], v[152:153], off offset:512 nt
	global_load_dwordx2 v[166:167], v[152:153], off offset:1024 nt
	global_load_dwordx2 v[152:153], v[152:153], off offset:1536 nt
	s_waitcnt vmcnt(6)
	s_nop 0
	v_lshlrev_b32_e32 v168, 16, v160
	v_and_b32_e32 v169, 0xffff0000, v160
	v_lshlrev_b32_e32 v160, 16, v161
	v_and_b32_e32 v161, 0xffff0000, v161
	v_pk_mul_f32 v[160:161], v[102:103], v[160:161]
	v_pk_mul_f32 v[168:169], v[100:101], v[168:169]
	s_nop 0
	v_cvt_pk_bf16_f32 v168, v168, v169
	v_cvt_pk_bf16_f32 v169, v160, v161
	v_add_u32_e32 v160, s4, v150
	v_ashrrev_i32_e32 v161, 31, v160
	v_lshlrev_b64 v[160:161], 11, v[160:161]
	v_lshl_add_u64 v[160:161], s[14:15], 0, v[160:161]
	v_lshl_add_u64 v[160:161], v[160:161], 0, s[28:29]
	v_lshl_add_u64 v[160:161], v[160:161], 0, s[38:39]
	v_lshl_add_u64 v[160:161], v[160:161], 0, v[140:141]
	v_mov_b32_e32 v196, v168
	v_mov_b32_e32 v197, v169
	v_lshlrev_b32_e32 v168, 16, v162
	v_and_b32_e32 v169, 0xffff0000, v162
	v_lshlrev_b32_e32 v162, 16, v163
	v_and_b32_e32 v163, 0xffff0000, v163
	v_pk_mul_f32 v[162:163], v[98:99], v[162:163]
	v_pk_mul_f32 v[168:169], v[96:97], v[168:169]
	s_nop 0
	v_cvt_pk_bf16_f32 v168, v168, v169
	v_cvt_pk_bf16_f32 v169, v162, v163
	v_lshlrev_b32_e32 v162, 16, v164
	v_and_b32_e32 v163, 0xffff0000, v164
	v_lshlrev_b32_e32 v164, 16, v165
	v_and_b32_e32 v165, 0xffff0000, v165
	v_pk_mul_f32 v[164:165], v[70:71], v[164:165]
	v_pk_mul_f32 v[162:163], v[68:69], v[162:163]
	v_mov_b32_e32 v198, v168
	v_mov_b32_e32 v199, v169
	v_cvt_pk_bf16_f32 v162, v162, v163
	v_cvt_pk_bf16_f32 v163, v164, v165
	v_mov_b32_e32 v200, v162
	v_mov_b32_e32 v201, v163
	v_lshlrev_b32_e32 v162, 16, v158
	v_and_b32_e32 v163, 0xffff0000, v158
	v_lshlrev_b32_e32 v158, 16, v159
	v_and_b32_e32 v159, 0xffff0000, v159
	v_pk_mul_f32 v[158:159], v[66:67], v[158:159]
	v_pk_mul_f32 v[162:163], v[64:65], v[162:163]
	s_nop 0
	v_cvt_pk_bf16_f32 v162, v162, v163
	v_cvt_pk_bf16_f32 v163, v158, v159
	v_mov_b32_e32 v202, v162
	v_mov_b32_e32 v203, v163
	s_nop 1
	v_permlane32_swap_b32_e32 v196, v198
	v_permlane32_swap_b32_e32 v197, v199
	v_permlane32_swap_b32_e32 v200, v202
	v_permlane32_swap_b32_e32 v201, v203
	v_permlane16_swap_b32_e32 v196, v198
	v_permlane16_swap_b32_e32 v197, v199
	v_permlane16_swap_b32_e32 v200, v202
	v_permlane16_swap_b32_e32 v201, v203
	v_lshl_add_u64 v[204:205], v[160:161], 0, v[206:207]
	global_store_dwordx4 v[204:205], v[196:199], off sc1
	global_store_dwordx4 v[204:205], v[200:203], off offset:256 sc1
	v_lshl_add_u64 v[158:159], v[144:145], 0, s[48:49]
	global_load_dwordx2 v[160:161], v[158:159], off nt
	global_load_dwordx2 v[162:163], v[158:159], off offset:512 nt
	global_load_dwordx2 v[164:165], v[158:159], off offset:1024 nt
	global_load_dwordx2 v[158:159], v[158:159], off offset:1536 nt
	s_waitcnt vmcnt(6)
; __device__ __forceinline__ u32x2 pk4(f32x4 v) { u32x2 r; r.x = pk_bf16(v[0], v[1]); r.y = pk_bf16(v[2], v[3]); return r; }
; __device__ __forceinline__ f32x4 unpk4(u32x2 v) { return (f32x4){bf_lo(v.x), bf_hi(v.x), bf_lo(v.y), bf_hi(v.y)}; }
; __device__ __forceinline__ void tie4(u32x2 (&d)[4]) { asm volatile("" : "+v"(d[0]), "+v"(d[1]), "+v"(d[2]), "+v"(d[3])); }
;     template <int POS> __device__ __forceinline__ void run(f32x4 (&acc)[2][2][4][2], const Unit& u, const bf16_t* F, int wr, int wc, int fr, int fq) const {
;     ...
; #pragma unroll
;         for (int e = 0; e < 8; ++e) {
;             if (POS < 2) { if (e < 7) asm volatile("s_waitcnt vmcnt(4)" ::: "memory"); else asm volatile("s_waitcnt vmcnt(0)" ::: "memory"); }
;             else { if (e == 0) asm volatile("s_waitcnt vmcnt(4)" ::: "memory"); else if (e < 7) asm volatile("s_waitcnt vmcnt(8)" ::: "memory"); else asm volatile("s_waitcnt vmcnt(4)" ::: "memory"); }
;             tie4(ga[e & 1]);
;             const int ai = e >> 2, m = e & 3;
; #pragma unroll
;             for (int k = 0; k < 4; ++k) { const int bj = k >> 1, n = k & 1;
;                 const f32x4 f = unpk4(ga[e & 1][k]);
;                 if (POS < 2) acc[ai][bj][m][n] *= f;
;                 else *(u32x2*)(MERGED + (size_t)(u.pm * 256 + ai * 128 + wr * 64 + m * 16 + fr) * 1024 + u.pn * 256 + bj * 128 + wc * 32 + n * 16 + fq * 4) = pk4(f * acc[ai][bj][m][n]);
;             }
;             if (e + 2 < 8) ld4(ga[e & 1], s0 + (e + 2) * 256);
;         }
	s_nop 0
	v_lshlrev_b32_e32 v168, 16, v154
	v_and_b32_e32 v169, 0xffff0000, v154
	v_lshlrev_b32_e32 v154, 16, v155
	v_and_b32_e32 v155, 0xffff0000, v155
	v_pk_mul_f32 v[154:155], v[62:63], v[154:155]
	v_pk_mul_f32 v[168:169], v[60:61], v[168:169]
	s_nop 0
	v_cvt_pk_bf16_f32 v168, v168, v169
	v_cvt_pk_bf16_f32 v169, v154, v155
	v_add_u32_e32 v154, 0x80, v142
	v_ashrrev_i32_e32 v155, 31, v154
	v_lshlrev_b64 v[154:155], 11, v[154:155]
	v_lshl_add_u64 v[154:155], s[14:15], 0, v[154:155]
	v_lshl_add_u64 v[154:155], v[154:155], 0, s[28:29]
	v_lshl_add_u64 v[154:155], v[154:155], 0, s[38:39]
	v_lshl_add_u64 v[154:155], v[154:155], 0, v[140:141]
	v_mov_b32_e32 v172, v168
	v_mov_b32_e32 v173, v169
	v_lshlrev_b32_e32 v168, 16, v156
	v_and_b32_e32 v169, 0xffff0000, v156
	v_lshlrev_b32_e32 v156, 16, v157
	v_and_b32_e32 v157, 0xffff0000, v157
	v_pk_mul_f32 v[156:157], v[58:59], v[156:157]
	v_pk_mul_f32 v[168:169], v[56:57], v[168:169]
	s_nop 0
	v_cvt_pk_bf16_f32 v168, v168, v169
	v_cvt_pk_bf16_f32 v169, v156, v157
	v_lshlrev_b32_e32 v156, 16, v166
	v_and_b32_e32 v157, 0xffff0000, v166
	v_lshlrev_b32_e32 v166, 16, v167
	v_and_b32_e32 v167, 0xffff0000, v167
	v_pk_mul_f32 v[166:167], v[30:31], v[166:167]
	v_pk_mul_f32 v[156:157], v[28:29], v[156:157]
	v_mov_b32_e32 v174, v168
	v_mov_b32_e32 v175, v169
	v_cvt_pk_bf16_f32 v156, v156, v157
	v_cvt_pk_bf16_f32 v157, v166, v167
	v_mov_b32_e32 v176, v156
	v_mov_b32_e32 v177, v157
	v_lshlrev_b32_e32 v156, 16, v152
	v_and_b32_e32 v157, 0xffff0000, v152
	v_lshlrev_b32_e32 v152, 16, v153
	v_and_b32_e32 v153, 0xffff0000, v153
	v_pk_mul_f32 v[152:153], v[26:27], v[152:153]
	v_pk_mul_f32 v[156:157], v[24:25], v[156:157]
	s_nop 0
	v_cvt_pk_bf16_f32 v156, v156, v157
	v_cvt_pk_bf16_f32 v157, v152, v153
	v_mov_b32_e32 v178, v156
	v_mov_b32_e32 v179, v157
	s_nop 1
	v_permlane32_swap_b32_e32 v172, v174
	v_permlane32_swap_b32_e32 v173, v175
	v_permlane32_swap_b32_e32 v176, v178
	v_permlane32_swap_b32_e32 v177, v179
	v_permlane16_swap_b32_e32 v172, v174
	v_permlane16_swap_b32_e32 v173, v175
	v_permlane16_swap_b32_e32 v176, v178
	v_permlane16_swap_b32_e32 v177, v179
	v_lshl_add_u64 v[204:205], v[154:155], 0, v[206:207]
	global_store_dwordx4 v[204:205], v[172:175], off sc1
	global_store_dwordx4 v[204:205], v[176:179], off offset:256 sc1
	v_lshl_add_u64 v[152:153], v[144:145], 0, s[50:51]
	global_load_dwordx2 v[154:155], v[152:153], off nt
	global_load_dwordx2 v[156:157], v[152:153], off offset:512 nt
	global_load_dwordx2 v[166:167], v[152:153], off offset:1024 nt
	global_load_dwordx2 v[152:153], v[152:153], off offset:1536 nt
	s_waitcnt vmcnt(6)
	v_lshl_add_u64 v[144:145], v[144:145], 0, s[52:53]
	v_lshlrev_b32_e32 v168, 16, v160
	v_and_b32_e32 v169, 0xffff0000, v160
	v_lshlrev_b32_e32 v160, 16, v161
	v_and_b32_e32 v161, 0xffff0000, v161
	v_pk_mul_f32 v[160:161], v[54:55], v[160:161]
	v_pk_mul_f32 v[168:169], v[52:53], v[168:169]
	s_nop 0
	v_cvt_pk_bf16_f32 v168, v168, v169
	v_cvt_pk_bf16_f32 v169, v160, v161
	v_add_u32_e32 v160, 0x90, v142
	v_ashrrev_i32_e32 v161, 31, v160
	v_lshlrev_b64 v[160:161], 11, v[160:161]
	v_lshl_add_u64 v[160:161], s[14:15], 0, v[160:161]
	v_lshl_add_u64 v[160:161], v[160:161], 0, s[28:29]
	v_lshl_add_u64 v[160:161], v[160:161], 0, s[38:39]
	v_lshl_add_u64 v[160:161], v[160:161], 0, v[140:141]
	v_mov_b32_e32 v180, v168
	v_mov_b32_e32 v181, v169
	v_lshlrev_b32_e32 v168, 16, v162
	v_and_b32_e32 v169, 0xffff0000, v162
	v_lshlrev_b32_e32 v162, 16, v163
	v_and_b32_e32 v163, 0xffff0000, v163
	v_pk_mul_f32 v[162:163], v[50:51], v[162:163]
	v_pk_mul_f32 v[168:169], v[48:49], v[168:169]
	s_nop 0
	v_cvt_pk_bf16_f32 v168, v168, v169
	v_cvt_pk_bf16_f32 v169, v162, v163
	v_lshlrev_b32_e32 v162, 16, v164
	v_and_b32_e32 v163, 0xffff0000, v164
	v_lshlrev_b32_e32 v164, 16, v165
	v_and_b32_e32 v165, 0xffff0000, v165
	v_pk_mul_f32 v[164:165], v[22:23], v[164:165]
	v_pk_mul_f32 v[162:163], v[20:21], v[162:163]
	v_mov_b32_e32 v182, v168
	v_mov_b32_e32 v183, v169
	v_cvt_pk_bf16_f32 v162, v162, v163
	v_cvt_pk_bf16_f32 v163, v164, v165
	v_mov_b32_e32 v184, v162
	v_mov_b32_e32 v185, v163
	v_lshlrev_b32_e32 v162, 16, v158
	v_and_b32_e32 v163, 0xffff0000, v158
	v_lshlrev_b32_e32 v158, 16, v159
	v_and_b32_e32 v159, 0xffff0000, v159
	v_pk_mul_f32 v[158:159], v[18:19], v[158:159]
	v_pk_mul_f32 v[162:163], v[16:17], v[162:163]
	s_nop 0
	v_cvt_pk_bf16_f32 v162, v162, v163
	v_cvt_pk_bf16_f32 v163, v158, v159
	v_mov_b32_e32 v186, v162
	v_mov_b32_e32 v187, v163
	s_nop 1
	v_permlane32_swap_b32_e32 v180, v182
	v_permlane32_swap_b32_e32 v181, v183
	v_permlane32_swap_b32_e32 v184, v186
	v_permlane32_swap_b32_e32 v185, v187
	v_permlane16_swap_b32_e32 v180, v182
	v_permlane16_swap_b32_e32 v181, v183
	v_permlane16_swap_b32_e32 v184, v186
	v_permlane16_swap_b32_e32 v185, v187
	v_lshl_add_u64 v[204:205], v[160:161], 0, v[206:207]
	global_store_dwordx4 v[204:205], v[180:183], off sc1
	global_store_dwordx4 v[204:205], v[184:187], off offset:256 sc1
	global_load_dwordx2 v[158:159], v[144:145], off nt
	global_load_dwordx2 v[160:161], v[144:145], off offset:512 nt
	global_load_dwordx2 v[162:163], v[144:145], off offset:1024 nt
	global_load_dwordx2 v[144:145], v[144:145], off offset:1536 nt
	s_waitcnt vmcnt(6)
; __device__ __forceinline__ u32x2 pk4(f32x4 v) { u32x2 r; r.x = pk_bf16(v[0], v[1]); r.y = pk_bf16(v[2], v[3]); return r; }
; __device__ __forceinline__ f32x4 unpk4(u32x2 v) { return (f32x4){bf_lo(v.x), bf_hi(v.x), bf_lo(v.y), bf_hi(v.y)}; }
; __device__ __forceinline__ void tie4(u32x2 (&d)[4]) { asm volatile("" : "+v"(d[0]), "+v"(d[1]), "+v"(d[2]), "+v"(d[3])); }
;     template <int POS> __device__ __forceinline__ void run(f32x4 (&acc)[2][2][4][2], const Unit& u, const bf16_t* F, int wr, int wc, int fr, int fq) const {
;     ...
; #pragma unroll
;         for (int e = 0; e < 8; ++e) {
;             if (POS < 2) { if (e < 7) asm volatile("s_waitcnt vmcnt(4)" ::: "memory"); else asm volatile("s_waitcnt vmcnt(0)" ::: "memory"); }
;             else { if (e == 0) asm volatile("s_waitcnt vmcnt(4)" ::: "memory"); else if (e < 7) asm volatile("s_waitcnt vmcnt(8)" ::: "memory"); else asm volatile("s_waitcnt vmcnt(4)" ::: "memory"); }
;             tie4(ga[e & 1]);
;             const int ai = e >> 2, m = e & 3;
; #pragma unroll
;             for (int k = 0; k < 4; ++k) { const int bj = k >> 1, n = k & 1;
;                 const f32x4 f = unpk4(ga[e & 1][k]);
;                 if (POS < 2) acc[ai][bj][m][n] *= f;
;                 else *(u32x2*)(MERGED + (size_t)(u.pm * 256 + ai * 128 + wr * 64 + m * 16 + fr) * 1024 + u.pn * 256 + bj * 128 + wc * 32 + n * 16 + fq * 4) = pk4(f * acc[ai][bj][m][n]);
;             }
;             if (e + 2 < 8) ld4(ga[e & 1], s0 + (e + 2) * 256);
;         }
	s_nop 0
	v_lshlrev_b32_e32 v164, 16, v154
	v_and_b32_e32 v165, 0xffff0000, v154
	v_lshlrev_b32_e32 v154, 16, v155
	v_and_b32_e32 v155, 0xffff0000, v155
	v_pk_mul_f32 v[154:155], v[46:47], v[154:155]
	v_pk_mul_f32 v[164:165], v[44:45], v[164:165]
	s_nop 0
	v_cvt_pk_bf16_f32 v164, v164, v165
	v_cvt_pk_bf16_f32 v165, v154, v155
	v_add_u32_e32 v154, 0xa0, v142
	v_ashrrev_i32_e32 v155, 31, v154
	v_lshlrev_b64 v[154:155], 11, v[154:155]
	v_lshl_add_u64 v[154:155], s[14:15], 0, v[154:155]
	v_lshl_add_u64 v[154:155], v[154:155], 0, s[28:29]
	v_lshl_add_u64 v[154:155], v[154:155], 0, s[38:39]
	v_lshl_add_u64 v[154:155], v[154:155], 0, v[140:141]
	v_mov_b32_e32 v188, v164
	v_mov_b32_e32 v189, v165
	v_lshlrev_b32_e32 v164, 16, v156
	v_and_b32_e32 v165, 0xffff0000, v156
	v_lshlrev_b32_e32 v156, 16, v157
	v_and_b32_e32 v157, 0xffff0000, v157
	v_pk_mul_f32 v[156:157], v[42:43], v[156:157]
	v_pk_mul_f32 v[164:165], v[40:41], v[164:165]
	v_add_u32_e32 v142, 0xb0, v142
	v_cvt_pk_bf16_f32 v164, v164, v165
	v_cvt_pk_bf16_f32 v165, v156, v157
	v_mov_b32_e32 v190, v164
	v_mov_b32_e32 v191, v165
	v_lshlrev_b32_e32 v156, 16, v166
	v_and_b32_e32 v157, 0xffff0000, v166
	v_lshlrev_b32_e32 v164, 16, v167
	v_and_b32_e32 v165, 0xffff0000, v167
	v_pk_mul_f32 v[164:165], v[14:15], v[164:165]
	v_pk_mul_f32 v[156:157], v[12:13], v[156:157]
	v_ashrrev_i32_e32 v143, 31, v142
	v_cvt_pk_bf16_f32 v156, v156, v157
	v_cvt_pk_bf16_f32 v157, v164, v165
	v_mov_b32_e32 v192, v156
	v_mov_b32_e32 v193, v157
	v_lshlrev_b32_e32 v156, 16, v152
	v_and_b32_e32 v157, 0xffff0000, v152
	v_lshlrev_b32_e32 v152, 16, v153
	v_and_b32_e32 v153, 0xffff0000, v153
	v_pk_mul_f32 v[152:153], v[10:11], v[152:153]
	v_pk_mul_f32 v[156:157], v[8:9], v[156:157]
	v_lshlrev_b64 v[142:143], 11, v[142:143]
	v_cvt_pk_bf16_f32 v156, v156, v157
	v_cvt_pk_bf16_f32 v157, v152, v153
	v_mov_b32_e32 v194, v156
	v_mov_b32_e32 v195, v157
	s_nop 1
	v_permlane32_swap_b32_e32 v188, v190
	v_permlane32_swap_b32_e32 v189, v191
	v_permlane32_swap_b32_e32 v192, v194
	v_permlane32_swap_b32_e32 v193, v195
	v_permlane16_swap_b32_e32 v188, v190
	v_permlane16_swap_b32_e32 v189, v191
	v_permlane16_swap_b32_e32 v192, v194
	v_permlane16_swap_b32_e32 v193, v195
	v_lshl_add_u64 v[204:205], v[154:155], 0, v[206:207]
	global_store_dwordx4 v[204:205], v[188:191], off sc1
	global_store_dwordx4 v[204:205], v[192:195], off offset:256 sc1
	v_lshl_add_u64 v[142:143], s[14:15], 0, v[142:143]
	s_waitcnt vmcnt(2)
	v_lshl_add_u64 v[142:143], v[142:143], 0, s[28:29]
	v_lshlrev_b32_e32 v152, 16, v158
	v_and_b32_e32 v153, 0xffff0000, v158
	v_lshlrev_b32_e32 v154, 16, v159
	v_and_b32_e32 v155, 0xffff0000, v159
	v_pk_mul_f32 v[154:155], v[38:39], v[154:155]
	v_pk_mul_f32 v[152:153], v[36:37], v[152:153]
	v_lshl_add_u64 v[142:143], v[142:143], 0, s[38:39]
	v_cvt_pk_bf16_f32 v152, v152, v153
	v_cvt_pk_bf16_f32 v153, v154, v155
	v_lshl_add_u64 v[142:143], v[142:143], 0, v[140:141]
	v_mov_b32_e32 v196, v152
	v_mov_b32_e32 v197, v153
	v_lshlrev_b32_e32 v152, 16, v160
	v_and_b32_e32 v153, 0xffff0000, v160
	v_lshlrev_b32_e32 v154, 16, v161
	v_and_b32_e32 v155, 0xffff0000, v161
	v_pk_mul_f32 v[154:155], v[34:35], v[154:155]
	v_pk_mul_f32 v[152:153], v[32:33], v[152:153]
	s_nop 0
	v_cvt_pk_bf16_f32 v152, v152, v153
	v_cvt_pk_bf16_f32 v153, v154, v155
	v_mov_b32_e32 v198, v152
	v_mov_b32_e32 v199, v153
	v_lshlrev_b32_e32 v152, 16, v162
	v_and_b32_e32 v153, 0xffff0000, v162
	v_lshlrev_b32_e32 v154, 16, v163
	v_and_b32_e32 v155, 0xffff0000, v163
	v_pk_mul_f32 v[154:155], v[6:7], v[154:155]
	v_pk_mul_f32 v[152:153], v[4:5], v[152:153]
	s_nop 0
	v_cvt_pk_bf16_f32 v152, v152, v153
	v_cvt_pk_bf16_f32 v153, v154, v155
	v_mov_b32_e32 v200, v152
	v_mov_b32_e32 v201, v153
	v_lshlrev_b32_e32 v152, 16, v144
	v_and_b32_e32 v153, 0xffff0000, v144
	v_lshlrev_b32_e32 v144, 16, v145
	v_and_b32_e32 v145, 0xffff0000, v145
	v_pk_mul_f32 v[144:145], v[2:3], v[144:145]
	v_pk_mul_f32 v[152:153], v[0:1], v[152:153]
	s_nop 0
	v_cvt_pk_bf16_f32 v152, v152, v153
	v_cvt_pk_bf16_f32 v153, v144, v145
	v_mov_b32_e32 v202, v152
	v_mov_b32_e32 v203, v153
	s_nop 1
	v_permlane32_swap_b32_e32 v196, v198
	v_permlane32_swap_b32_e32 v197, v199
	v_permlane32_swap_b32_e32 v200, v202
	v_permlane32_swap_b32_e32 v201, v203
	v_permlane16_swap_b32_e32 v196, v198
	v_permlane16_swap_b32_e32 v197, v199
	v_permlane16_swap_b32_e32 v200, v202
	v_permlane16_swap_b32_e32 v201, v203
	v_lshl_add_u64 v[204:205], v[142:143], 0, v[206:207]
	global_store_dwordx4 v[204:205], v[196:199], off sc1
	global_store_dwordx4 v[204:205], v[200:203], off offset:256 sc1
	s_cbranch_execz .LBB0_552
